# in-proj fourth-round idle workgroups run their heavy differential-attention item early (batch-local barrier after round 3, partial tiles first); compress items first in phase X
# speedup vs baseline: 1.0090x; 1.0090x over previous
; __device__ void item_diff(const Params& p, int layer, int b, int hd, int qt, unsigned char* smem) {
;     ...
;   const float lam = P_LAM[layer];
;   const float lam_init = 0.8f - 0.6f * expf(-0.3f * (float)layer);
;   const u16* hb = P_H + (size_t)b * SEQ * HS;
;   const u16* vt = P_VT + ((size_t)b * VTC + hd * 64) * SEQ;
; __device__ void phase_x(const Params& p, int layer, unsigned char* smem) {
;   constexpr int NA = 8 * 4 * 32, NC = 2 * 8 * 2 * 8, NBI = 8 * 2 * 32;
;   const int G = gridDim.x;
;   for (int i = blockIdx.x; i < NA / 2; i += G) {
; #pragma unroll 1
;     for (int h = 0; h < 2; ++h) {
;       int it = h ? (NA - 1 - i) : i;
;       int qt = 31 - (it >> 5); int r = it & 31; int b = r >> 2, hd = r & 3;
;       item_diff(p, layer, b, hd, qt, smem);
;     }
;   }
.LBB0_192:
	s_and_b64 vcc, exec, s[0:1]
	s_cbranch_vccz .LBB0_280
	v_readlane_b32 s0, v253, 3
	v_readlane_b32 s1, v253, 4
	s_load_dword s8, s[0:1], 0x0
	v_readlane_b32 s0, v254, 2
	v_readlane_b32 s1, v254, 3
	s_andn2_b64 vcc, exec, s[0:1]
	s_mov_b64 s[60:61], 0x200
	v_readlane_b32 s18, v255, 60
	s_cmp_lg_u32 s18, 1
	s_cbranch_scc1 .Lxh1_done
	v_readlane_b32 s18, v255, 63
	s_cmp_eq_u32 s18, 0
	s_cbranch_scc1 .LBB0_229
.Lxh1_done:
	s_cbranch_vccnz .LBB0_229
	v_readlane_b32 s0, v255, 21
	s_mov_b32 s18, s0
	v_cvt_f32_i32_e32 v0, s18
	s_mov_b32 s0, 0x3fb8aa3b
	v_readlane_b32 s1, v255, 22
	s_ashr_i32 s19, s18, 31
	v_mul_f32_e32 v0, 0xbe99999a, v0
	v_mul_f32_e32 v2, 0x3fb8aa3b, v0
	v_fma_f32 v3, v0, s0, -v2
	v_rndne_f32_e32 v4, v2
	v_fmac_f32_e32 v3, 0x32a5705f, v0
	v_sub_f32_e32 v2, v2, v4
	v_add_f32_e32 v2, v2, v3
	v_cvt_i32_f32_e32 v4, v4
	v_exp_f32_e32 v2, v2
	s_mov_b32 s0, 0xc2ce8ed0
	v_cmp_ngt_f32_e32 vcc, s0, v0
	s_mov_b32 s0, 0x42b17218
	v_ldexp_f32 v2, v2, v4
	v_cndmask_b32_e32 v2, 0, v2, vcc
	v_cmp_nlt_f32_e32 vcc, s0, v0
	s_mov_b32 s0, s18
	s_lshl_b32 s6, s18, 6
	v_writelane_b32 v255, s0, 21
	s_ashr_i32 s7, s6, 31
	v_mov_b32_e32 v0, 0x7f800000
	v_writelane_b32 v255, s1, 22
	s_lshl_b64 s[0:1], s[18:19], 2
	v_readlane_b32 s18, v254, 0
	v_readlane_b32 s19, v254, 1
	s_add_u32 s0, s18, s0
	v_cndmask_b32_e32 v0, v0, v2, vcc
	v_mov_b32_e32 v2, 0xbf4ccccd
	s_addc_u32 s1, s19, s1
	s_lshl_b64 s[6:7], s[6:7], 2
	v_readlane_b32 s40, v253, 12
	v_fmamk_f32 v0, v0, 0x3f19999a, v2
	v_readlane_b32 s41, v253, 13
	s_add_u32 s6, s40, s6
	v_add_f32_e32 v142, 1.0, v0
	s_addc_u32 s7, s41, s7
	v_readlane_b32 s9, v253, 0
	v_readlane_b32 s42, v253, 14
	v_readlane_b32 s43, v253, 15
	v_readlane_b32 s44, v253, 16
	v_readlane_b32 s45, v253, 17
	v_readlane_b32 s46, v253, 18
	v_readlane_b32 s47, v253, 19
	v_readlane_b32 s48, v253, 20
	v_readlane_b32 s49, v253, 21
	v_readlane_b32 s50, v253, 22
	v_readlane_b32 s51, v253, 23
	v_readlane_b32 s52, v253, 24
	v_readlane_b32 s53, v253, 25
	v_readlane_b32 s54, v253, 26
	v_readlane_b32 s55, v253, 27
	s_branch .LBB0_196

; __device__ void phase_x(const Params& p, int layer, unsigned char* smem) {
;     ...
;   for (int i = blockIdx.x; i < NA / 2; i += G) {
; #pragma unroll 1
;     for (int h = 0; h < 2; ++h) {
;       int it = h ? (NA - 1 - i) : i;
;       int qt = 31 - (it >> 5); int r = it & 31; int b = r >> 2, hd = r & 3;
;       item_diff(p, layer, b, hd, qt, smem);
.Ldiffbal_done:
	s_mov_b64 s[18:19], -1
	v_readlane_b32 s24, v255, 61
	s_cmp_eq_u32 s24, 0
	s_cbranch_scc1 .Ld1_done
	s_mov_b64 s[18:19], 0
	s_cmp_eq_u32 s24, 1
	s_cselect_b32 s12, s9, s12
	s_cbranch_scc1 .Ld1_done
	v_writelane_b32 v255, s87, 61
.Ld1_done:
	s_branch .LBB0_199
.LBB0_197:
	s_mov_b64 s[60:61], 0x200

; __device__ void phase_x(const Params& p, int layer, unsigned char* smem) {
;     ...
;   for (int i = blockIdx.x; i < NA / 2; i += G) {
; #pragma unroll 1
;     for (int h = 0; h < 2; ++h) {
;       int it = h ? (NA - 1 - i) : i;
;       int qt = 31 - (it >> 5); int r = it & 31; int b = r >> 2, hd = r & 3;
;       item_diff(p, layer, b, hd, qt, smem);
;     }
;   }
;   for (int i = blockIdx.x; i < NC; i += G) {
;     int t = i; int ct = t & 7; t >>= 3; int g = t & 1; t >>= 1; int b = t & 7; int kv = t >> 3;
;     item_compress(p, layer, kv, b, g, ct, smem);
.LBB0_229:
	v_readlane_b32 s18, v255, 61
	s_cmp_lg_u32 s18, 1
	s_cbranch_scc1 .Ld2_no
	s_mov_b32 s18, 2
	v_writelane_b32 v255, s18, 61
	v_writelane_b32 v255, s87, 63
	v_readlane_b32 s52, v255, 19
	v_readlane_b32 s53, v255, 20
	s_add_i32 s52, s52, -1
	s_branch .LBB0_498
.Ld2_no:
	v_readlane_b32 s0, v254, 11
	v_readlane_b32 s1, v254, 12
	s_andn2_b64 vcc, exec, s[0:1]
	v_readlane_b32 s18, v255, 63
	s_cmp_eq_u32 s18, 1
	s_cbranch_scc1 .LBB0_238
	s_cbranch_vccnz .LBB0_238
	v_readlane_b32 s0, v255, 21
	v_readlane_b32 s1, v255, 22
	s_mov_b32 s24, s0
	s_ashr_i32 s25, s0, 31
	s_lshl_b64 s[0:1], s[24:25], 13
	s_lshl_b64 s[6:7], s[24:25], 19
	s_add_u32 s6, s88, s6
	s_addc_u32 s7, s89, s7
	s_mov_b32 s18, s24
	s_mul_i32 s9, s24, 0xfff84000
	s_mul_hi_i32 s12, s24, 0xfff84000
	v_writelane_b32 v255, s18, 21
	s_add_u32 s9, s6, s9
	s_addc_u32 s12, s7, s12
	v_writelane_b32 v255, s19, 22
	v_readlane_b32 s24, v253, 0
	s_branch .LBB0_232

; __device__ void phase_x(const Params& p, int layer, unsigned char* smem) {
;     ...
;   for (int i = blockIdx.x; i < NC; i += G) {
;     int t = i; int ct = t & 7; t >>= 3; int g = t & 1; t >>= 1; int b = t & 7; int kv = t >> 3;
;     item_compress(p, layer, kv, b, g, ct, smem);
;   }
.LBB0_238:
	s_waitcnt lgkmcnt(0)
	v_readlane_b32 s18, v255, 60
	s_cmp_lg_u32 s18, 1
	s_cbranch_scc1 .Lxh2_done
	v_readlane_b32 s18, v255, 63
	s_cmp_lg_u32 s18, 0
	s_cbranch_scc1 .Lxh2_p1
	s_mov_b32 s18, 1
	v_writelane_b32 v255, s18, 63
	v_readlane_b32 s18, v253, 0
	s_cmpk_ge_u32 s18, 0x100
	s_cbranch_scc1 .Lxh2_go
	s_waitcnt vmcnt(0) lgkmcnt(0)
	s_barrier
	v_cmp_eq_u32_e32 vcc, 0, v210
	s_and_saveexec_b64 s[0:1], vcc
	s_cbranch_execz .Lxh2_e
	v_readlane_b32 s6, v255, 58
	v_readlane_b32 s7, v255, 59
	v_mov_b32_e32 v0, 1
	s_nop 3
	global_atomic_add v0, v1, v0, s[6:7] offset:64 sc0
	s_waitcnt vmcnt(0)
	v_readfirstlane_b32 s18, v0
	s_and_b32 s18, s18, 31
	s_cmp_lg_u32 s18, 31
	s_cbranch_scc1 .Lxh2_e
	v_mov_b32_e32 v0, 1
	global_atomic_add v1, v0, s[6:7] offset:1056

; __device__ void phase_x(const Params& p, int layer, unsigned char* smem) {
;     ...
;   {
;     const int nfree = G - NC;
;     int i0, step;
;     if (nfree >= 64) { i0 = (int)blockIdx.x - NC; step = nfree; if (i0 < 0) i0 = NBI; }
;     else { i0 = blockIdx.x; step = G; }
;     for (int i = i0; i < NBI; i += step) {
;       int t = i; int qt = t & 31; t >>= 5; int g = t & 1; int b = t >> 1;
;       item_swa(p, layer, b, g, qt, smem);
;     }
;   }
.Lxh2_go:
	v_readlane_b32 s52, v255, 19
	v_readlane_b32 s53, v255, 20
	s_branch .LBB0_10
.Lxh2_p1:
	v_writelane_b32 v255, s87, 63
.Lxh2_done:
	s_cmpk_gt_i32 s8, 0x13f
	s_cselect_b64 s[0:1], -1, 0
	s_and_b64 s[6:7], s[0:1], exec
	v_readlane_b32 s6, v253, 0
	v_readlane_b32 s7, v254, 13
	s_cselect_b32 s9, s7, s6
	s_cmpk_gt_i32 s9, 0x1ff
	s_movk_i32 s74, 0x3fff
	s_movk_i32 s75, 0x210
	s_mov_b32 s77, 0x40000
	s_mov_b32 s78, 0x60000
	s_cbranch_scc1 .LBB0_280
	s_add_i32 s6, s8, 0xffffff00
	s_and_b64 s[0:1], s[0:1], exec
	v_readlane_b32 s0, v255, 21
	s_cselect_b32 s8, s6, s8
	s_lshl_b32 s12, s0, 2
	s_mov_b32 s24, s9
	v_readlane_b32 s1, v255, 22
	s_branch .LBB0_242

; __device__ void phase_inproj(const Params& p, int layer, unsigned char* smem) {
;     ...
;   for (int idx = loc; idx < 8 * NT_IN; idx += nloc) {
;     int grp = idx / (2 * NT_IN), within = idx % (2 * NT_IN);
;     int nt = within >> 1, mt = xcd * 8 + grp * 2 + (within & 1);
;     int vbase = -1;
;     if (nt == 4) vbase = 0; else if (nt == 5) vbase = 128; else if (nt == 11) vbase = 256;
;     else if (nt == 21) vbase = 384; else if (nt == 23) vbase = 512;
;     if (vbase >= 0) gemm_tile2<1>(P_XN, DM, W, DM, DM, mt * 256, nt * 128, P_VT, vbase, nullptr, nullptr, smem);
;     else gemm_tile2<0>(P_XN, DM, W, DM, DM, mt * 256, nt * 128, P_H, 0, nullptr, nullptr, smem);
;   }
.LBB0_286:
	s_add_i32 s29, s29, s12
	v_readlane_b32 s0, v255, 60
	s_cmp_lg_u32 s0, 1
	s_cbranch_scc1 .Limid_done
	s_cmpk_lt_u32 s29, 0xc0
	s_cbranch_scc1 .Limid_done
	s_cmpk_gt_u32 s29, 0xff
	s_cbranch_scc1 .Limid_done
	s_waitcnt vmcnt(0) lgkmcnt(0)
	s_barrier
	v_cmp_eq_u32_e32 vcc, 0, v210
	s_and_saveexec_b64 s[0:1], vcc
	s_cbranch_execz .Limid_x
	v_readlane_b32 s6, v255, 58
	v_readlane_b32 s7, v255, 59
	v_mov_b32_e32 v0, 1
	s_nop 3
	global_atomic_add v0, v1, v0, s[6:7] sc0
	s_waitcnt vmcnt(0)
	v_readfirstlane_b32 s24, v0
	s_lshr_b32 s25, s24, 6
	s_and_b32 s24, s24, 63
	s_cmp_lg_u32 s24, 63
	s_cbranch_scc1 .Limid_poll
	v_mov_b32_e32 v0, 1
	global_atomic_add v1, v0, s[6:7] offset:1024
	s_branch .Limid_acq
.Limid_poll:
	s_mov_b32 s24, 0
.Limid_p:
	s_sleep 1
	global_load_dword v0, v1, s[6:7] offset:1024 sc1
	s_waitcnt vmcnt(0)
	v_readfirstlane_b32 s18, v0
	s_cmp_gt_u32 s18, s25
	s_cbranch_scc1 .Limid_acq
	s_add_i32 s24, s24, 1
	s_cmp_lt_u32 s24, 0x100000
	s_cbranch_scc1 .Limid_p

; __device__ void phase_inproj(const Params& p, int layer, unsigned char* smem) {
;     ...
;   for (int idx = loc; idx < 8 * NT_IN; idx += nloc) {
;     int grp = idx / (2 * NT_IN), within = idx % (2 * NT_IN);
;     int nt = within >> 1, mt = xcd * 8 + grp * 2 + (within & 1);
.Limid_done:
	s_cmpk_gt_u32 s29, 0xe7
	s_cbranch_scc1 .LBB0_330
.LBB0_287:
	s_cmpk_gt_u32 s29, 7
	s_cbranch_scc0 .Ltile_pad
	s_add_i32 s24, s29, -8
	s_lshr_b32 s0, s24, 3
	s_mul_i32 s0, s0, 37
	s_lshr_b32 s25, s0, 8
	s_mul_i32 s0, s25, 56
	s_sub_i32 s24, s24, s0
	s_branch .Ltile_dec
.Ltile_pad:
	s_mov_b32 s0, s29
	s_lshr_b32 s25, s0, 1
	s_and_b32 s24, s0, 1
	s_add_i32 s24, s24, 56

; #define LAS __attribute__((address_space(3)))
; __global__ void __launch_bounds__(256, 2) hybrid_megakernel(Params p, int ph_lo, int ph_hi) {
;     ...
;   if (threadIdx.x == 0) xb_words = make_uint4(0u, 0u, 0u, 0u);
;   __syncthreads();
;   XcdBarrier xb = xcd_barrier_post((unsigned*)P_CTR, (volatile LAS unsigned*)&xb_words);
;   for (int ph = ph_lo; ph < ph_hi; ++ph) {
;     if (ph == 1) continue;
;     run_phase(p, ph, smem);
;     if (ph + 1 < ph_hi) {
;       if (ph_hi > 1000) cg::this_grid().sync();
;       xcd_barrier(xb);
;     }
.LBB0_498:
	s_add_i32 s12, s52, 1
	s_cmp_ge_i32 s12, s53
	s_cbranch_scc1 .LBB0_9
	s_cmp_lg_u32 s52, 0
	s_cbranch_scc1 .Llb_later
	v_writelane_b32 v255, s87, 60
	v_writelane_b32 v255, s87, 61
	v_writelane_b32 v255, s87, 63
	s_getreg_b32 s0, hwreg(HW_REG_XCC_ID, 0, 4)
	s_lshl_b32 s0, 1, s0
	v_readlane_b32 s1, v253, 0
	s_and_b32 s1, s1, 7
	s_lshl_b32 s1, s1, 2
	s_add_u32 s8, s88, 0x3fc0
	s_addc_u32 s9, s89, 0
	s_add_u32 s8, s8, s1
	s_addc_u32 s9, s9, 0
	v_cmp_eq_u32_e32 vcc, 0, v210
	s_and_saveexec_b64 s[6:7], vcc
	v_mov_b32_e32 v0, s0
	global_atomic_or v1, v0, s[8:9]
	s_mov_b64 exec, s[6:7]
	s_branch .Llb_global

; __global__ void __launch_bounds__(256, 2) hybrid_megakernel(Params p, int ph_lo, int ph_hi) {
;     ...
;     if (ph + 1 < ph_hi) {
;       if (ph_hi > 1000) cg::this_grid().sync();
;       xcd_barrier(xb);
;     }
.Llb_have:
	s_cmp_lg_u32 s0, 1
	s_cbranch_scc1 .Llb_global
	s_lshr_b32 s1, 0x21080, s52
	s_bitcmp1_b32 s1, 0
	s_cbranch_scc0 .Lea_no
	v_readlane_b32 s1, v253, 0
	s_cmpk_lt_u32 s1, 0x140
	s_cbranch_scc1 .Lea_no
	v_readlane_b32 s1, v255, 61
	s_cmp_eq_u32 s1, 2
	s_cbranch_scc1 .Lea_no
	s_mov_b32 s1, 1
	v_writelane_b32 v255, s1, 61
	v_writelane_b32 v255, s1, 63
	s_add_i32 s52, s52, 1
	s_branch .LBB0_10
.Lea_no:
	s_lshr_b32 s1, 0x42108, s52
	s_bitcmp1_b32 s1, 0
	s_cbranch_scc1 .Lxbar
	s_lshr_b32 s1, 0x1ffffc, s52
	s_bitcmp1_b32 s1, 0
	s_cbranch_scc0 .Llb_global
	s_waitcnt vmcnt(0) lgkmcnt(0)
	s_barrier
	v_cmp_eq_u32_e32 vcc, 0, v210
	s_and_saveexec_b64 s[0:1], vcc
	s_cbranch_execz .Llbar_x
	v_readlane_b32 s6, v255, 58
	v_readlane_b32 s7, v255, 59
	v_mov_b32_e32 v0, 1
	s_nop 3
	global_atomic_add v0, v1, v0, s[6:7] sc0
	s_waitcnt vmcnt(0)
	v_readfirstlane_b32 s8, v0
	s_lshr_b32 s9, s8, 6
	s_and_b32 s8, s8, 63
	s_cmp_lg_u32 s8, 63
	s_cbranch_scc1 .Llbar_poll
	v_mov_b32_e32 v0, 1
	global_atomic_add v1, v0, s[6:7] offset:1024
	s_branch .Llbar_acq

; __device__ __forceinline__ unsigned xb_ld(unsigned* p)              { return __hip_atomic_load(p, __ATOMIC_RELAXED, __HIP_MEMORY_SCOPE_AGENT); }
; __device__ __forceinline__ unsigned xb_add(unsigned* p, unsigned v) { return __hip_atomic_fetch_add(p, v, __ATOMIC_RELAXED, __HIP_MEMORY_SCOPE_AGENT); }
; #define XB_SPIN(cond, bar) do { unsigned _sp = 0; while (cond) { __builtin_amdgcn_s_sleep(1); \
;     if ((++_sp & 255u) == 0u) { if (xb_ld(&(bar)[XB_TMO])) break; if (_sp > XB_SPIN_CAP) { atomicAdd(&(bar)[XB_TMO], 1u); break; } } } } while (0)
; __device__ __forceinline__ void xcd_barrier(const XcdBarrier& b) {
;     asm volatile("s_waitcnt vmcnt(0)" ::: "memory");
;     __syncthreads();
;     if (threadIdx.x == 0) {
;         unsigned* bar = b.bar;
;         __builtin_amdgcn_s_waitcnt(0);
;         unsigned nloc = b.st[0], nx = b.st[1];
;         if (nloc == 0u) { xcd_barrier_complete(bar, b.x, nloc, nx); b.st[0] = nloc; b.st[1] = nx; }
;         const unsigned old = xb_add(&bar[XB_XSUB(b.x)], 1u);
;         const unsigned gen = old / nloc;
;         if (old + 1u == (gen + 1u) * nloc) {
;             __builtin_amdgcn_fence(__ATOMIC_RELEASE, "agent");
;             asm volatile("s_waitcnt vmcnt(0)" ::: "memory");
;             const unsigned og = xb_add(&bar[XB_TOP], 1u);
;             const unsigned tg = og / nx;
;             if (og + 1u == (tg + 1u) * nx) xb_add(&bar[XB_TOPGEN], 1u);
;             else XB_SPIN(xb_ld(&bar[XB_TOPGEN]) == tg, bar);
;             __builtin_amdgcn_fence(__ATOMIC_ACQUIRE, "agent");
;             xb_add(&bar[XB_XGEN(b.x)], 1u);
;             asm volatile("s_waitcnt vmcnt(0)" ::: "memory");
;         } else {
;             XB_SPIN(xb_ld(&bar[XB_XGEN(b.x)]) == gen, bar);
;             __builtin_amdgcn_fence(__ATOMIC_ACQUIRE, "agent");
;             asm volatile("s_waitcnt vmcnt(0)" ::: "memory");
;         }
.Lxbar:
	s_waitcnt vmcnt(0) lgkmcnt(0)
	s_barrier
	v_cmp_eq_u32_e32 vcc, 0, v210
	s_and_saveexec_b64 s[0:1], vcc
	s_cbranch_execz .Llbar_x
	v_readlane_b32 s6, v255, 58
	v_readlane_b32 s7, v255, 59
	s_add_i32 s9, s52, 2
	s_mul_i32 s9, s9, 0x3334
	s_lshr_b32 s9, s9, 16
.Lxbar_poll:
	s_mov_b32 s8, 0
